# k12 + V^T projection epilogues (VT0, VT1): column scales via LDS table (64 -> 2 ssq loads per lane per tile, rsq form)
# speedup vs baseline: 1.0298x; 1.0034x over previous
;     __device__ __forceinline__ void operator()(const f32x4 (&acc)[2][2][4][2], const Unit& u, int wr, int wc, int fr, int fq) const {
;         const int row0 = u.pm * BM + wr * 64 + fr, col0 = u.pn * BM + wc * 32 + 8 * fq;
;         f32x4 cs[2][2];
; #pragma unroll
;         for (int bj = 0; bj < 2; ++bj)
; #pragma unroll
;             for (int n = 0; n < 2; ++n) {
; #pragma unroll
;                 for (int e = 0; e < 4; ++e) cs[bj][n][e] = 1.0f / sqrtf(ssq_sum(ssq_in + (size_t)(col0 + bj * HALF + 4 * n + e) * 16) * inv_dim + EPS); }
.LBB0_503:
	v_readlane_b32 vcc_lo, v254, 7
	v_mbcnt_lo_u32_b32 v170, -1, 0
	v_mbcnt_hi_u32_b32 v170, -1, v170
	v_lshrrev_b32_e32 v171, 1, v170
	v_lshl_add_u32 v171, vcc_lo, 5, v171
	v_and_b32_e32 v172, 1, v170
	v_lshl_add_u32 v173, s2, 8, v171
	v_lshlrev_b32_e32 v173, 6, v173
	v_lshl_add_u32 v173, v172, 5, v173
	global_load_dwordx4 v[174:177], v173, s[18:19]
	global_load_dwordx4 v[178:181], v173, s[18:19] offset:16
	v_lshl_or_b32 v182, s2, 8, v164
	v_lshl_add_u32 v183, s42, 8, v162
	v_lshlrev_b32_e32 v183, 16, v183
	v_lshl_add_u32 v183, v182, 1, v183
	v_lshlrev_b32_e32 v171, 2, v171
	v_add_u32_e32 v171, 0x20100, v171
	v_lshlrev_b32_e32 v172, 2, v164
	v_add_u32_e32 v172, 0x20100, v172
	s_waitcnt vmcnt(0)
	v_pk_add_f32 v[174:175], v[174:175], v[176:177]
	v_pk_add_f32 v[178:179], v[178:179], v[180:181]
	v_pk_add_f32 v[174:175], v[174:175], v[178:179]
	v_add_f32_e32 v174, v174, v175
	s_nop 1
	v_add_f32_dpp v174, v174, v174 quad_perm:[1,0,3,2] row_mask:0xf bank_mask:0xf
	v_fmamk_f32 v174, v174, 0x3a800000, v168
	v_rsq_f32_e32 v174, v174
	s_nop 0
	ds_write_b32 v171, v174
	s_waitcnt lgkmcnt(0)
	s_barrier
; __device__ __forceinline__ unsigned cvtpk(float lo, float hi) { f32x2_t v = {lo, hi}; bf16x2_t b = __builtin_convertvector(v, bf16x2_t); return __builtin_bit_cast(unsigned, b); }
;     __device__ __forceinline__ void operator()(const f32x4 (&acc)[2][2][4][2], const Unit& u, int wr, int wc, int fr, int fq) const {
;     ...
; #pragma unroll
;         for (int ai = 0; ai < 2; ++ai)
; #pragma unroll
;             for (int m = 0; m < 4; ++m) {
;                 const int row = row0 + ai * HALF + m * 16;
; #pragma unroll
;                 for (int bj = 0; bj < 2; ++bj) {
;                     const f32x4 v0 = acc[ai][bj][m][0] * cs[bj][0], v1 = acc[ai][bj][m][1] * cs[bj][1];
;                     u32x4 w; w.x = cvtpk(v0[0], v0[1]); w.y = cvtpk(v0[2], v0[3]); w.z = cvtpk(v1[0], v1[1]); w.w = cvtpk(v1[2], v1[3]);
;                     *(u32x4*)(O + (size_t)row * ldc + col0 + bj * HALF) = w;
;                 }
;             }
	ds_read_b128 v[146:149], v172
	ds_read_b128 v[150:153], v172 offset:16
	ds_read_b128 v[154:157], v172 offset:512
	ds_read_b128 v[158:161], v172 offset:528
	s_waitcnt lgkmcnt(0)
	v_pk_mul_f32 v[124:125], v[124:125], v[146:147]
	v_pk_mul_f32 v[126:127], v[126:127], v[148:149]
	v_pk_mul_f32 v[120:121], v[120:121], v[150:151]
	v_pk_mul_f32 v[122:123], v[122:123], v[152:153]
	v_pk_mul_f32 v[116:117], v[116:117], v[154:155]
	v_pk_mul_f32 v[118:119], v[118:119], v[156:157]
	v_pk_mul_f32 v[104:105], v[104:105], v[158:159]
	v_pk_mul_f32 v[106:107], v[106:107], v[160:161]
	v_cvt_pk_bf16_f32 v124, v124, v125
	v_cvt_pk_bf16_f32 v125, v126, v127
	v_cvt_pk_bf16_f32 v126, v120, v121
	v_cvt_pk_bf16_f32 v127, v122, v123
	v_cvt_pk_bf16_f32 v116, v116, v117
	v_cvt_pk_bf16_f32 v117, v118, v119
	v_cvt_pk_bf16_f32 v118, v104, v105
	v_cvt_pk_bf16_f32 v119, v106, v107
	global_store_dwordx4 v183, v[124:127], s[14:15]
	global_store_dwordx4 v183, v[116:119], s[14:15] offset:256
	v_pk_mul_f32 v[112:113], v[112:113], v[146:147]
	v_pk_mul_f32 v[114:115], v[114:115], v[148:149]
	v_pk_mul_f32 v[108:109], v[108:109], v[150:151]
	v_pk_mul_f32 v[110:111], v[110:111], v[152:153]
	v_pk_mul_f32 v[96:97], v[96:97], v[154:155]
	v_pk_mul_f32 v[98:99], v[98:99], v[156:157]
	v_pk_mul_f32 v[88:89], v[88:89], v[158:159]
	v_pk_mul_f32 v[90:91], v[90:91], v[160:161]
	v_cvt_pk_bf16_f32 v112, v112, v113
	v_cvt_pk_bf16_f32 v113, v114, v115
	v_cvt_pk_bf16_f32 v114, v108, v109
	v_cvt_pk_bf16_f32 v115, v110, v111
	v_cvt_pk_bf16_f32 v96, v96, v97
	v_cvt_pk_bf16_f32 v97, v98, v99
	v_cvt_pk_bf16_f32 v98, v88, v89
	v_cvt_pk_bf16_f32 v99, v90, v91
	v_add_u32_e32 v184, 0x100000, v183
	global_store_dwordx4 v184, v[112:115], s[14:15]
	global_store_dwordx4 v184, v[96:99], s[14:15] offset:256
	v_pk_mul_f32 v[100:101], v[100:101], v[146:147]
	v_pk_mul_f32 v[102:103], v[102:103], v[148:149]
	v_pk_mul_f32 v[92:93], v[92:93], v[150:151]
	v_pk_mul_f32 v[94:95], v[94:95], v[152:153]
	v_pk_mul_f32 v[80:81], v[80:81], v[154:155]
	v_pk_mul_f32 v[82:83], v[82:83], v[156:157]
	v_pk_mul_f32 v[72:73], v[72:73], v[158:159]
	v_pk_mul_f32 v[74:75], v[74:75], v[160:161]
	v_cvt_pk_bf16_f32 v100, v100, v101
	v_cvt_pk_bf16_f32 v101, v102, v103
	v_cvt_pk_bf16_f32 v102, v92, v93
	v_cvt_pk_bf16_f32 v103, v94, v95
	v_cvt_pk_bf16_f32 v80, v80, v81
	v_cvt_pk_bf16_f32 v81, v82, v83
	v_cvt_pk_bf16_f32 v82, v72, v73
	v_cvt_pk_bf16_f32 v83, v74, v75
	v_add_u32_e32 v184, 0x200000, v183
	global_store_dwordx4 v184, v[100:103], s[14:15]
	global_store_dwordx4 v184, v[80:83], s[14:15] offset:256
	v_pk_mul_f32 v[84:85], v[84:85], v[146:147]
	v_pk_mul_f32 v[86:87], v[86:87], v[148:149]
	v_pk_mul_f32 v[76:77], v[76:77], v[150:151]
	v_pk_mul_f32 v[78:79], v[78:79], v[152:153]
	v_pk_mul_f32 v[68:69], v[68:69], v[154:155]
	v_pk_mul_f32 v[70:71], v[70:71], v[156:157]
	v_pk_mul_f32 v[64:65], v[64:65], v[158:159]
	v_pk_mul_f32 v[66:67], v[66:67], v[160:161]
	v_cvt_pk_bf16_f32 v84, v84, v85
	v_cvt_pk_bf16_f32 v85, v86, v87
	v_cvt_pk_bf16_f32 v86, v76, v77
	v_cvt_pk_bf16_f32 v87, v78, v79
	v_cvt_pk_bf16_f32 v68, v68, v69
	v_cvt_pk_bf16_f32 v69, v70, v71
	v_cvt_pk_bf16_f32 v70, v64, v65
	v_cvt_pk_bf16_f32 v71, v66, v67
	v_add_u32_e32 v184, 0x300000, v183
	global_store_dwordx4 v184, v[84:87], s[14:15]
	global_store_dwordx4 v184, v[68:71], s[14:15] offset:256
	v_pk_mul_f32 v[60:61], v[60:61], v[146:147]
	v_pk_mul_f32 v[62:63], v[62:63], v[148:149]
	v_pk_mul_f32 v[56:57], v[56:57], v[150:151]
	v_pk_mul_f32 v[58:59], v[58:59], v[152:153]
	v_pk_mul_f32 v[48:49], v[48:49], v[154:155]
	v_pk_mul_f32 v[50:51], v[50:51], v[156:157]
	v_pk_mul_f32 v[40:41], v[40:41], v[158:159]
	v_pk_mul_f32 v[42:43], v[42:43], v[160:161]
	v_cvt_pk_bf16_f32 v60, v60, v61
	v_cvt_pk_bf16_f32 v61, v62, v63
	v_cvt_pk_bf16_f32 v62, v56, v57
	v_cvt_pk_bf16_f32 v63, v58, v59
	v_cvt_pk_bf16_f32 v48, v48, v49
	v_cvt_pk_bf16_f32 v49, v50, v51
	v_cvt_pk_bf16_f32 v50, v40, v41
	v_cvt_pk_bf16_f32 v51, v42, v43
	v_add_u32_e32 v184, 0x800000, v183
	global_store_dwordx4 v184, v[60:63], s[14:15]
	global_store_dwordx4 v184, v[48:51], s[14:15] offset:256
	v_pk_mul_f32 v[52:53], v[52:53], v[146:147]
	v_pk_mul_f32 v[54:55], v[54:55], v[148:149]
	v_pk_mul_f32 v[44:45], v[44:45], v[150:151]
	v_pk_mul_f32 v[46:47], v[46:47], v[152:153]
	v_pk_mul_f32 v[32:33], v[32:33], v[154:155]
	v_pk_mul_f32 v[34:35], v[34:35], v[156:157]
	v_pk_mul_f32 v[24:25], v[24:25], v[158:159]
	v_pk_mul_f32 v[26:27], v[26:27], v[160:161]
	v_cvt_pk_bf16_f32 v52, v52, v53
	v_cvt_pk_bf16_f32 v53, v54, v55
	v_cvt_pk_bf16_f32 v54, v44, v45
	v_cvt_pk_bf16_f32 v55, v46, v47
	v_cvt_pk_bf16_f32 v32, v32, v33
	v_cvt_pk_bf16_f32 v33, v34, v35
	v_cvt_pk_bf16_f32 v34, v24, v25
	v_cvt_pk_bf16_f32 v35, v26, v27
	v_add_u32_e32 v184, 0x900000, v183
	global_store_dwordx4 v184, v[52:55], s[14:15]
	global_store_dwordx4 v184, v[32:35], s[14:15] offset:256
	v_pk_mul_f32 v[36:37], v[36:37], v[146:147]
	v_pk_mul_f32 v[38:39], v[38:39], v[148:149]
	v_pk_mul_f32 v[28:29], v[28:29], v[150:151]
	v_pk_mul_f32 v[30:31], v[30:31], v[152:153]
	v_pk_mul_f32 v[16:17], v[16:17], v[154:155]
	v_pk_mul_f32 v[18:19], v[18:19], v[156:157]
	v_pk_mul_f32 v[8:9], v[8:9], v[158:159]
	v_pk_mul_f32 v[10:11], v[10:11], v[160:161]
	v_cvt_pk_bf16_f32 v36, v36, v37
	v_cvt_pk_bf16_f32 v37, v38, v39
	v_cvt_pk_bf16_f32 v38, v28, v29
	v_cvt_pk_bf16_f32 v39, v30, v31
	v_cvt_pk_bf16_f32 v16, v16, v17
	v_cvt_pk_bf16_f32 v17, v18, v19
	v_cvt_pk_bf16_f32 v18, v8, v9
	v_cvt_pk_bf16_f32 v19, v10, v11
	v_add_u32_e32 v184, 0xa00000, v183
	global_store_dwordx4 v184, v[36:39], s[14:15]
	global_store_dwordx4 v184, v[16:19], s[14:15] offset:256
	v_pk_mul_f32 v[20:21], v[20:21], v[146:147]
	v_pk_mul_f32 v[22:23], v[22:23], v[148:149]
	v_pk_mul_f32 v[12:13], v[12:13], v[150:151]
	v_pk_mul_f32 v[14:15], v[14:15], v[152:153]
	v_pk_mul_f32 v[4:5], v[4:5], v[154:155]
	v_pk_mul_f32 v[6:7], v[6:7], v[156:157]
	v_pk_mul_f32 v[0:1], v[0:1], v[158:159]
	v_pk_mul_f32 v[2:3], v[2:3], v[160:161]
	v_cvt_pk_bf16_f32 v20, v20, v21
	v_cvt_pk_bf16_f32 v21, v22, v23
	v_cvt_pk_bf16_f32 v22, v12, v13
	v_cvt_pk_bf16_f32 v23, v14, v15
	v_cvt_pk_bf16_f32 v4, v4, v5
	v_cvt_pk_bf16_f32 v5, v6, v7
	v_cvt_pk_bf16_f32 v6, v0, v1
	v_cvt_pk_bf16_f32 v7, v2, v3
	v_add_u32_e32 v184, 0xb00000, v183
	global_store_dwordx4 v184, v[20:23], s[14:15]
	global_store_dwordx4 v184, v[4:7], s[14:15] offset:256
	s_andn2_b64 vcc, exec, s[6:7]
	s_mov_b64 s[6:7], -1
	s_cbranch_vccnz .LBB0_492
	s_andn2_b64 vcc, exec, s[12:13]
	s_cbranch_vccnz .LBB0_491
	s_barrier
	s_branch .LBB0_491

;     __device__ __forceinline__ void operator()(const f32x4 (&acc)[2][2][4][2], const Unit& u, int wr, int wc, int fr, int fq) const {
;         const int row0 = u.pm * BM + wr * 64 + fr, col0 = u.pn * BM + wc * 32 + 8 * fq;
;         f32x4 cs[2][2];
; #pragma unroll
;         for (int bj = 0; bj < 2; ++bj)
; #pragma unroll
;             for (int n = 0; n < 2; ++n) {
; #pragma unroll
;                 for (int e = 0; e < 4; ++e) cs[bj][n][e] = 1.0f / sqrtf(ssq_sum(ssq_in + (size_t)(col0 + bj * HALF + 4 * n + e) * 16) * inv_dim + EPS); }
.LBB0_1573:
	v_readlane_b32 vcc_lo, v254, 7
	v_mbcnt_lo_u32_b32 v166, -1, 0
	v_mbcnt_hi_u32_b32 v166, -1, v166
	v_lshrrev_b32_e32 v167, 1, v166
	v_lshl_add_u32 v167, vcc_lo, 5, v167
	v_and_b32_e32 v168, 1, v166
	v_lshl_add_u32 v169, s2, 8, v167
	v_lshlrev_b32_e32 v169, 6, v169
	v_lshl_add_u32 v169, v168, 5, v169
	global_load_dwordx4 v[170:173], v169, s[14:15]
	global_load_dwordx4 v[174:177], v169, s[14:15] offset:16
	v_lshl_or_b32 v178, s2, 8, v160
	v_lshl_add_u32 v179, s42, 8, v158
	v_lshlrev_b32_e32 v179, 16, v179
	v_lshl_add_u32 v179, v178, 1, v179
	v_lshlrev_b32_e32 v167, 2, v167
	v_add_u32_e32 v167, 0x20100, v167
	v_lshlrev_b32_e32 v168, 2, v160
	v_add_u32_e32 v168, 0x20100, v168
	s_waitcnt vmcnt(0)
	v_pk_add_f32 v[170:171], v[170:171], v[172:173]
	v_pk_add_f32 v[174:175], v[174:175], v[176:177]
	v_pk_add_f32 v[170:171], v[170:171], v[174:175]
	v_add_f32_e32 v170, v170, v171
	s_nop 1
	v_add_f32_dpp v170, v170, v170 quad_perm:[1,0,3,2] row_mask:0xf bank_mask:0xf
	v_fmamk_f32 v170, v170, 0x3b800000, v164
	v_rsq_f32_e32 v170, v170
	s_nop 0
	ds_write_b32 v167, v170
	s_waitcnt lgkmcnt(0)
	s_barrier
; __device__ __forceinline__ unsigned cvtpk(float lo, float hi) { f32x2_t v = {lo, hi}; bf16x2_t b = __builtin_convertvector(v, bf16x2_t); return __builtin_bit_cast(unsigned, b); }
;     __device__ __forceinline__ void operator()(const f32x4 (&acc)[2][2][4][2], const Unit& u, int wr, int wc, int fr, int fq) const {
;         const int row0 = u.pm * BM + wr * 64 + fr, col0 = u.pn * BM + wc * 32 + 8 * fq;
;         f32x4 cs[2][2];
; #pragma unroll
;         for (int bj = 0; bj < 2; ++bj)
; #pragma unroll
;             for (int n = 0; n < 2; ++n) {
; #pragma unroll
;                 for (int e = 0; e < 4; ++e) cs[bj][n][e] = 1.0f / sqrtf(ssq_sum(ssq_in + (size_t)(col0 + bj * HALF + 4 * n + e) * 16) * inv_dim + EPS); }
; #pragma unroll
;         for (int ai = 0; ai < 2; ++ai)
; #pragma unroll
;             for (int m = 0; m < 4; ++m) {
;                 const int row = row0 + ai * HALF + m * 16;
; #pragma unroll
;                 for (int bj = 0; bj < 2; ++bj) {
;                     const f32x4 v0 = acc[ai][bj][m][0] * cs[bj][0], v1 = acc[ai][bj][m][1] * cs[bj][1];
;                     u32x4 w; w.x = cvtpk(v0[0], v0[1]); w.y = cvtpk(v0[2], v0[3]); w.z = cvtpk(v1[0], v1[1]); w.w = cvtpk(v1[2], v1[3]);
;                     *(u32x4*)(O + (size_t)row * ldc + col0 + bj * HALF) = w;
;                 }
;             }
	ds_read_b128 v[142:145], v168
	ds_read_b128 v[146:149], v168 offset:16
	ds_read_b128 v[150:153], v168 offset:512
	ds_read_b128 v[154:157], v168 offset:528
	s_waitcnt lgkmcnt(0)
	v_pk_mul_f32 v[124:125], v[124:125], v[142:143]
	v_pk_mul_f32 v[126:127], v[126:127], v[144:145]
	v_pk_mul_f32 v[120:121], v[120:121], v[146:147]
	v_pk_mul_f32 v[122:123], v[122:123], v[148:149]
	v_pk_mul_f32 v[116:117], v[116:117], v[150:151]
	v_pk_mul_f32 v[118:119], v[118:119], v[152:153]
	v_pk_mul_f32 v[104:105], v[104:105], v[154:155]
	v_pk_mul_f32 v[106:107], v[106:107], v[156:157]
	v_cvt_pk_bf16_f32 v124, v124, v125
	v_cvt_pk_bf16_f32 v125, v126, v127
	v_cvt_pk_bf16_f32 v126, v120, v121
	v_cvt_pk_bf16_f32 v127, v122, v123
	v_cvt_pk_bf16_f32 v116, v116, v117
	v_cvt_pk_bf16_f32 v117, v118, v119
	v_cvt_pk_bf16_f32 v118, v104, v105
	v_cvt_pk_bf16_f32 v119, v106, v107
	global_store_dwordx4 v179, v[124:127], s[18:19]
	global_store_dwordx4 v179, v[116:119], s[18:19] offset:256
	v_pk_mul_f32 v[112:113], v[112:113], v[142:143]
	v_pk_mul_f32 v[114:115], v[114:115], v[144:145]
	v_pk_mul_f32 v[108:109], v[108:109], v[146:147]
	v_pk_mul_f32 v[110:111], v[110:111], v[148:149]
	v_pk_mul_f32 v[96:97], v[96:97], v[150:151]
	v_pk_mul_f32 v[98:99], v[98:99], v[152:153]
	v_pk_mul_f32 v[88:89], v[88:89], v[154:155]
	v_pk_mul_f32 v[90:91], v[90:91], v[156:157]
	v_cvt_pk_bf16_f32 v112, v112, v113
	v_cvt_pk_bf16_f32 v113, v114, v115
	v_cvt_pk_bf16_f32 v114, v108, v109
	v_cvt_pk_bf16_f32 v115, v110, v111
	v_cvt_pk_bf16_f32 v96, v96, v97
	v_cvt_pk_bf16_f32 v97, v98, v99
	v_cvt_pk_bf16_f32 v98, v88, v89
	v_cvt_pk_bf16_f32 v99, v90, v91
	v_add_u32_e32 v180, 0x100000, v179
	global_store_dwordx4 v180, v[112:115], s[18:19]
	global_store_dwordx4 v180, v[96:99], s[18:19] offset:256
	v_pk_mul_f32 v[100:101], v[100:101], v[142:143]
	v_pk_mul_f32 v[102:103], v[102:103], v[144:145]
	v_pk_mul_f32 v[92:93], v[92:93], v[146:147]
	v_pk_mul_f32 v[94:95], v[94:95], v[148:149]
	v_pk_mul_f32 v[80:81], v[80:81], v[150:151]
	v_pk_mul_f32 v[82:83], v[82:83], v[152:153]
	v_pk_mul_f32 v[72:73], v[72:73], v[154:155]
	v_pk_mul_f32 v[74:75], v[74:75], v[156:157]
	v_cvt_pk_bf16_f32 v100, v100, v101
	v_cvt_pk_bf16_f32 v101, v102, v103
	v_cvt_pk_bf16_f32 v102, v92, v93
	v_cvt_pk_bf16_f32 v103, v94, v95
	v_cvt_pk_bf16_f32 v80, v80, v81
	v_cvt_pk_bf16_f32 v81, v82, v83
	v_cvt_pk_bf16_f32 v82, v72, v73
	v_cvt_pk_bf16_f32 v83, v74, v75
	v_add_u32_e32 v180, 0x200000, v179
	global_store_dwordx4 v180, v[100:103], s[18:19]
	global_store_dwordx4 v180, v[80:83], s[18:19] offset:256
	v_pk_mul_f32 v[84:85], v[84:85], v[142:143]
	v_pk_mul_f32 v[86:87], v[86:87], v[144:145]
	v_pk_mul_f32 v[76:77], v[76:77], v[146:147]
	v_pk_mul_f32 v[78:79], v[78:79], v[148:149]
	v_pk_mul_f32 v[68:69], v[68:69], v[150:151]
	v_pk_mul_f32 v[70:71], v[70:71], v[152:153]
	v_pk_mul_f32 v[64:65], v[64:65], v[154:155]
	v_pk_mul_f32 v[66:67], v[66:67], v[156:157]
	v_cvt_pk_bf16_f32 v84, v84, v85
	v_cvt_pk_bf16_f32 v85, v86, v87
	v_cvt_pk_bf16_f32 v86, v76, v77
	v_cvt_pk_bf16_f32 v87, v78, v79
	v_cvt_pk_bf16_f32 v68, v68, v69
	v_cvt_pk_bf16_f32 v69, v70, v71
	v_cvt_pk_bf16_f32 v70, v64, v65
	v_cvt_pk_bf16_f32 v71, v66, v67
	v_add_u32_e32 v180, 0x300000, v179
	global_store_dwordx4 v180, v[84:87], s[18:19]
	global_store_dwordx4 v180, v[68:71], s[18:19] offset:256
	v_pk_mul_f32 v[60:61], v[60:61], v[142:143]
	v_pk_mul_f32 v[62:63], v[62:63], v[144:145]
	v_pk_mul_f32 v[56:57], v[56:57], v[146:147]
	v_pk_mul_f32 v[58:59], v[58:59], v[148:149]
	v_pk_mul_f32 v[48:49], v[48:49], v[150:151]
	v_pk_mul_f32 v[50:51], v[50:51], v[152:153]
	v_pk_mul_f32 v[40:41], v[40:41], v[154:155]
	v_pk_mul_f32 v[42:43], v[42:43], v[156:157]
	v_cvt_pk_bf16_f32 v60, v60, v61
	v_cvt_pk_bf16_f32 v61, v62, v63
	v_cvt_pk_bf16_f32 v62, v56, v57
	v_cvt_pk_bf16_f32 v63, v58, v59
	v_cvt_pk_bf16_f32 v48, v48, v49
	v_cvt_pk_bf16_f32 v49, v50, v51
	v_cvt_pk_bf16_f32 v50, v40, v41
	v_cvt_pk_bf16_f32 v51, v42, v43
	v_add_u32_e32 v180, 0x800000, v179
	global_store_dwordx4 v180, v[60:63], s[18:19]
	global_store_dwordx4 v180, v[48:51], s[18:19] offset:256
	v_pk_mul_f32 v[52:53], v[52:53], v[142:143]
	v_pk_mul_f32 v[54:55], v[54:55], v[144:145]
	v_pk_mul_f32 v[44:45], v[44:45], v[146:147]
	v_pk_mul_f32 v[46:47], v[46:47], v[148:149]
	v_pk_mul_f32 v[32:33], v[32:33], v[150:151]
	v_pk_mul_f32 v[34:35], v[34:35], v[152:153]
	v_pk_mul_f32 v[24:25], v[24:25], v[154:155]
	v_pk_mul_f32 v[26:27], v[26:27], v[156:157]
	v_cvt_pk_bf16_f32 v52, v52, v53
	v_cvt_pk_bf16_f32 v53, v54, v55
	v_cvt_pk_bf16_f32 v54, v44, v45
	v_cvt_pk_bf16_f32 v55, v46, v47
	v_cvt_pk_bf16_f32 v32, v32, v33
	v_cvt_pk_bf16_f32 v33, v34, v35
	v_cvt_pk_bf16_f32 v34, v24, v25
	v_cvt_pk_bf16_f32 v35, v26, v27
	v_add_u32_e32 v180, 0x900000, v179
	global_store_dwordx4 v180, v[52:55], s[18:19]
	global_store_dwordx4 v180, v[32:35], s[18:19] offset:256
	v_pk_mul_f32 v[36:37], v[36:37], v[142:143]
	v_pk_mul_f32 v[38:39], v[38:39], v[144:145]
	v_pk_mul_f32 v[28:29], v[28:29], v[146:147]
	v_pk_mul_f32 v[30:31], v[30:31], v[148:149]
	v_pk_mul_f32 v[16:17], v[16:17], v[150:151]
	v_pk_mul_f32 v[18:19], v[18:19], v[152:153]
	v_pk_mul_f32 v[8:9], v[8:9], v[154:155]
	v_pk_mul_f32 v[10:11], v[10:11], v[156:157]
	v_cvt_pk_bf16_f32 v36, v36, v37
	v_cvt_pk_bf16_f32 v37, v38, v39
	v_cvt_pk_bf16_f32 v38, v28, v29
	v_cvt_pk_bf16_f32 v39, v30, v31
	v_cvt_pk_bf16_f32 v16, v16, v17
	v_cvt_pk_bf16_f32 v17, v18, v19
	v_cvt_pk_bf16_f32 v18, v8, v9
	v_cvt_pk_bf16_f32 v19, v10, v11
	v_add_u32_e32 v180, 0xa00000, v179
	global_store_dwordx4 v180, v[36:39], s[18:19]
	global_store_dwordx4 v180, v[16:19], s[18:19] offset:256
	v_pk_mul_f32 v[20:21], v[20:21], v[142:143]
	v_pk_mul_f32 v[22:23], v[22:23], v[144:145]
	v_pk_mul_f32 v[12:13], v[12:13], v[146:147]
	v_pk_mul_f32 v[14:15], v[14:15], v[148:149]
	v_pk_mul_f32 v[4:5], v[4:5], v[150:151]
	v_pk_mul_f32 v[6:7], v[6:7], v[152:153]
	v_pk_mul_f32 v[0:1], v[0:1], v[154:155]
	v_pk_mul_f32 v[2:3], v[2:3], v[156:157]
	v_cvt_pk_bf16_f32 v20, v20, v21
	v_cvt_pk_bf16_f32 v21, v22, v23
	v_cvt_pk_bf16_f32 v22, v12, v13
	v_cvt_pk_bf16_f32 v23, v14, v15
	v_cvt_pk_bf16_f32 v4, v4, v5
	v_cvt_pk_bf16_f32 v5, v6, v7
	v_cvt_pk_bf16_f32 v6, v0, v1
	v_cvt_pk_bf16_f32 v7, v2, v3
	v_add_u32_e32 v180, 0xb00000, v179
	global_store_dwordx4 v180, v[20:23], s[18:19]
	global_store_dwordx4 v180, v[4:7], s[18:19] offset:256
	s_andn2_b64 vcc, exec, s[6:7]
	s_mov_b64 s[6:7], -1
	s_cbranch_vccnz .LBB0_1562
	s_andn2_b64 vcc, exec, s[16:17]
	s_cbranch_vccnz .LBB0_1561
	s_barrier
	s_branch .LBB0_1561
